# grid barrier: last cross-XCD arriver bumps all per-XCD release words itself (one polling hop less)
# speedup vs baseline: 1.0120x; 1.0083x over previous
; __device__ __forceinline__ unsigned xb_ld(unsigned* p)              { return __hip_atomic_load(p, __ATOMIC_RELAXED, __HIP_MEMORY_SCOPE_AGENT); }
; __device__ __forceinline__ unsigned xb_add(unsigned* p, unsigned v) { return __hip_atomic_fetch_add(p, v, __ATOMIC_RELAXED, __HIP_MEMORY_SCOPE_AGENT); }
; #define XB_SPIN(cond, bar) do { unsigned _sp = 0; while (cond) { \
;     if ((++_sp & 255u) == 0u) { if (xb_ld(&(bar)[XB_TMO])) break; if (_sp > XB_SPIN_CAP) { atomicAdd(&(bar)[XB_TMO], 1u); break; } } } } while (0)
; __device__ __forceinline__ void xcd_barrier(const XcdBarrier& b) {
;     ...
;         if (old + 1u == (gen + 1u) * nloc) {
;             __builtin_amdgcn_fence(__ATOMIC_RELEASE, "agent");
;             asm volatile("s_waitcnt vmcnt(0)" ::: "memory");
;             const unsigned og = xb_add(&bar[XB_TOP], 1u);
;             const unsigned tg = og / nx;
;             if (og + 1u == (tg + 1u) * nx) xb_add(&bar[XB_TOPGEN], 1u);
;             else XB_SPIN(xb_ld(&bar[XB_TOPGEN]) == tg, bar);
;             __builtin_amdgcn_fence(__ATOMIC_ACQUIRE, "agent");
;             xb_add(&bar[XB_XGEN(b.x)], 1u);
;             asm volatile("s_waitcnt vmcnt(0)" ::: "memory");
.LBB0_340:
	s_or_b64 exec, exec, s[6:7]
	s_and_saveexec_b64 s[6:7], s[8:9]
	s_cbranch_execz .LBB0_342
	global_atomic_add v[0:1], v213, off
	v_readlane_b32 s98, v245, 17
	v_readlane_b32 s99, v245, 18
	s_nop 3
	s_sub_u32 s98, s98, 0x1100
	s_subb_u32 s99, s99, 0
	global_atomic_add v169, v213, s[98:99]
	global_atomic_add v169, v213, s[98:99] offset:256
	global_atomic_add v169, v213, s[98:99] offset:512
	global_atomic_add v169, v213, s[98:99] offset:768
	global_atomic_add v169, v213, s[98:99] offset:1024
	global_atomic_add v169, v213, s[98:99] offset:1280
	global_atomic_add v169, v213, s[98:99] offset:1536
	global_atomic_add v169, v213, s[98:99] offset:1792
	global_atomic_add v169, v213, s[98:99] offset:2048
	global_atomic_add v169, v213, s[98:99] offset:2304
	global_atomic_add v169, v213, s[98:99] offset:2560
	global_atomic_add v169, v213, s[98:99] offset:2816
	global_atomic_add v169, v213, s[98:99] offset:3072
	global_atomic_add v169, v213, s[98:99] offset:3328
	global_atomic_add v169, v213, s[98:99] offset:3584
	global_atomic_add v169, v213, s[98:99] offset:3840
.LBB0_342:
	s_or_b64 exec, exec, s[6:7]
	s_mov_b64 s[6:7], exec
	v_mbcnt_lo_u32_b32 v0, s6, 0
	v_mbcnt_hi_u32_b32 v0, s7, v0
	v_cmp_eq_u32_e32 vcc, 0, v0
	s_waitcnt vmcnt(0)
	s_and_saveexec_b64 s[8:9], vcc
	s_cbranch_execz .LBB0_344
	s_bcnt1_i32_b64 s6, s[6:7]
	v_mov_b32_e32 v0, s6
	v_readlane_b32 s6, v245, 13
	v_readlane_b32 s7, v245, 14
	s_nop 4
.LBB0_344:
	s_or_b64 exec, exec, s[8:9]
	s_waitcnt vmcnt(0)

; __device__ __forceinline__ unsigned xb_ld(unsigned* p)              { return __hip_atomic_load(p, __ATOMIC_RELAXED, __HIP_MEMORY_SCOPE_AGENT); }
; __device__ __forceinline__ unsigned xb_add(unsigned* p, unsigned v) { return __hip_atomic_fetch_add(p, v, __ATOMIC_RELAXED, __HIP_MEMORY_SCOPE_AGENT); }
; #define XB_SPIN(cond, bar) do { unsigned _sp = 0; while (cond) { \
;     if ((++_sp & 255u) == 0u) { if (xb_ld(&(bar)[XB_TMO])) break; if (_sp > XB_SPIN_CAP) { atomicAdd(&(bar)[XB_TMO], 1u); break; } } } } while (0)
; __device__ __forceinline__ void xcd_barrier(const XcdBarrier& b) {
;     ...
;         if (old + 1u == (gen + 1u) * nloc) {
;             __builtin_amdgcn_fence(__ATOMIC_RELEASE, "agent");
;             asm volatile("s_waitcnt vmcnt(0)" ::: "memory");
;             const unsigned og = xb_add(&bar[XB_TOP], 1u);
;             const unsigned tg = og / nx;
;             if (og + 1u == (tg + 1u) * nx) xb_add(&bar[XB_TOPGEN], 1u);
;             else XB_SPIN(xb_ld(&bar[XB_TOPGEN]) == tg, bar);
;             __builtin_amdgcn_fence(__ATOMIC_ACQUIRE, "agent");
;             xb_add(&bar[XB_XGEN(b.x)], 1u);
;             asm volatile("s_waitcnt vmcnt(0)" ::: "memory");
.LBB0_423:
	s_or_b64 exec, exec, s[4:5]
	s_and_saveexec_b64 s[4:5], s[6:7]
	s_cbranch_execz .LBB0_425
	global_atomic_add v[0:1], v213, off
	v_readlane_b32 s98, v245, 17
	v_readlane_b32 s99, v245, 18
	s_nop 3
	s_sub_u32 s98, s98, 0x1100
	s_subb_u32 s99, s99, 0
	global_atomic_add v169, v213, s[98:99]
	global_atomic_add v169, v213, s[98:99] offset:256
	global_atomic_add v169, v213, s[98:99] offset:512
	global_atomic_add v169, v213, s[98:99] offset:768
	global_atomic_add v169, v213, s[98:99] offset:1024
	global_atomic_add v169, v213, s[98:99] offset:1280
	global_atomic_add v169, v213, s[98:99] offset:1536
	global_atomic_add v169, v213, s[98:99] offset:1792
	global_atomic_add v169, v213, s[98:99] offset:2048
	global_atomic_add v169, v213, s[98:99] offset:2304
	global_atomic_add v169, v213, s[98:99] offset:2560
	global_atomic_add v169, v213, s[98:99] offset:2816
	global_atomic_add v169, v213, s[98:99] offset:3072
	global_atomic_add v169, v213, s[98:99] offset:3328
	global_atomic_add v169, v213, s[98:99] offset:3584
	global_atomic_add v169, v213, s[98:99] offset:3840
.LBB0_425:
	s_or_b64 exec, exec, s[4:5]
	s_mov_b64 s[4:5], exec
	v_mbcnt_lo_u32_b32 v0, s4, 0
	v_mbcnt_hi_u32_b32 v0, s5, v0
	v_cmp_eq_u32_e32 vcc, 0, v0
	s_waitcnt vmcnt(0)
	s_and_saveexec_b64 s[6:7], vcc
	s_cbranch_execz .LBB0_427
	s_bcnt1_i32_b64 s4, s[4:5]
	v_readlane_b32 s0, v245, 13
	v_mov_b32_e32 v0, s4
	v_readlane_b32 s1, v245, 14
	s_nop 4
.LBB0_427:
	s_or_b64 exec, exec, s[6:7]
	s_waitcnt vmcnt(0)

; __device__ __forceinline__ unsigned xb_ld(unsigned* p)              { return __hip_atomic_load(p, __ATOMIC_RELAXED, __HIP_MEMORY_SCOPE_AGENT); }
; __device__ __forceinline__ unsigned xb_add(unsigned* p, unsigned v) { return __hip_atomic_fetch_add(p, v, __ATOMIC_RELAXED, __HIP_MEMORY_SCOPE_AGENT); }
; #define XB_SPIN(cond, bar) do { unsigned _sp = 0; while (cond) { \
;     if ((++_sp & 255u) == 0u) { if (xb_ld(&(bar)[XB_TMO])) break; if (_sp > XB_SPIN_CAP) { atomicAdd(&(bar)[XB_TMO], 1u); break; } } } } while (0)
; __device__ __forceinline__ void xcd_barrier(const XcdBarrier& b) {
;     ...
;         if (old + 1u == (gen + 1u) * nloc) {
;             __builtin_amdgcn_fence(__ATOMIC_RELEASE, "agent");
;             asm volatile("s_waitcnt vmcnt(0)" ::: "memory");
;             const unsigned og = xb_add(&bar[XB_TOP], 1u);
;             const unsigned tg = og / nx;
;             if (og + 1u == (tg + 1u) * nx) xb_add(&bar[XB_TOPGEN], 1u);
;             else XB_SPIN(xb_ld(&bar[XB_TOPGEN]) == tg, bar);
;             __builtin_amdgcn_fence(__ATOMIC_ACQUIRE, "agent");
;             xb_add(&bar[XB_XGEN(b.x)], 1u);
;             asm volatile("s_waitcnt vmcnt(0)" ::: "memory");
.LBB0_482:
	s_or_b64 exec, exec, s[4:5]
	s_mov_b64 s[4:5], exec
	v_mbcnt_lo_u32_b32 v0, s4, 0
	v_mbcnt_hi_u32_b32 v0, s5, v0
	v_cmp_eq_u32_e32 vcc, 0, v0
	s_waitcnt vmcnt(0)
	s_and_saveexec_b64 s[6:7], vcc
	s_cbranch_execz .LBB0_484
	s_bcnt1_i32_b64 s4, s[4:5]
	v_mov_b32_e32 v0, s4
	v_readlane_b32 s4, v245, 13
	v_readlane_b32 s5, v245, 14
	s_nop 4
.LBB0_484:
	s_or_b64 exec, exec, s[6:7]
	s_waitcnt vmcnt(0)

; __device__ __forceinline__ unsigned xb_ld(unsigned* p)              { return __hip_atomic_load(p, __ATOMIC_RELAXED, __HIP_MEMORY_SCOPE_AGENT); }
; __device__ __forceinline__ unsigned xb_add(unsigned* p, unsigned v) { return __hip_atomic_fetch_add(p, v, __ATOMIC_RELAXED, __HIP_MEMORY_SCOPE_AGENT); }
; #define XB_SPIN(cond, bar) do { unsigned _sp = 0; while (cond) { \
;     if ((++_sp & 255u) == 0u) { if (xb_ld(&(bar)[XB_TMO])) break; if (_sp > XB_SPIN_CAP) { atomicAdd(&(bar)[XB_TMO], 1u); break; } } } } while (0)
; __device__ __forceinline__ void xcd_barrier(const XcdBarrier& b) {
;     ...
;         if (old + 1u == (gen + 1u) * nloc) {
;             __builtin_amdgcn_fence(__ATOMIC_RELEASE, "agent");
;             asm volatile("s_waitcnt vmcnt(0)" ::: "memory");
;             const unsigned og = xb_add(&bar[XB_TOP], 1u);
;             const unsigned tg = og / nx;
;             if (og + 1u == (tg + 1u) * nx) xb_add(&bar[XB_TOPGEN], 1u);
;             else XB_SPIN(xb_ld(&bar[XB_TOPGEN]) == tg, bar);
;             __builtin_amdgcn_fence(__ATOMIC_ACQUIRE, "agent");
;             xb_add(&bar[XB_XGEN(b.x)], 1u);
;             asm volatile("s_waitcnt vmcnt(0)" ::: "memory");
.LBB0_537:
	s_or_b64 exec, exec, s[4:5]
	s_mov_b64 s[4:5], exec
	v_mbcnt_lo_u32_b32 v0, s4, 0
	v_mbcnt_hi_u32_b32 v0, s5, v0
	v_cmp_eq_u32_e32 vcc, 0, v0
	s_waitcnt vmcnt(0)
	s_and_saveexec_b64 s[6:7], vcc
	s_cbranch_execz .LBB0_539
	s_bcnt1_i32_b64 s4, s[4:5]
	v_mov_b32_e32 v0, s4
	v_readlane_b32 s4, v245, 13
	v_readlane_b32 s5, v245, 14
	s_nop 4
.LBB0_539:
	s_or_b64 exec, exec, s[6:7]
	s_waitcnt vmcnt(0)

; __device__ __forceinline__ unsigned xb_ld(unsigned* p)              { return __hip_atomic_load(p, __ATOMIC_RELAXED, __HIP_MEMORY_SCOPE_AGENT); }
; __device__ __forceinline__ unsigned xb_add(unsigned* p, unsigned v) { return __hip_atomic_fetch_add(p, v, __ATOMIC_RELAXED, __HIP_MEMORY_SCOPE_AGENT); }
; #define XB_SPIN(cond, bar) do { unsigned _sp = 0; while (cond) { \
;     if ((++_sp & 255u) == 0u) { if (xb_ld(&(bar)[XB_TMO])) break; if (_sp > XB_SPIN_CAP) { atomicAdd(&(bar)[XB_TMO], 1u); break; } } } } while (0)
; __device__ __forceinline__ void xcd_barrier(const XcdBarrier& b) {
;     ...
;         if (old + 1u == (gen + 1u) * nloc) {
;             __builtin_amdgcn_fence(__ATOMIC_RELEASE, "agent");
;             asm volatile("s_waitcnt vmcnt(0)" ::: "memory");
;             const unsigned og = xb_add(&bar[XB_TOP], 1u);
;             const unsigned tg = og / nx;
;             if (og + 1u == (tg + 1u) * nx) xb_add(&bar[XB_TOPGEN], 1u);
;             else XB_SPIN(xb_ld(&bar[XB_TOPGEN]) == tg, bar);
;             __builtin_amdgcn_fence(__ATOMIC_ACQUIRE, "agent");
;             xb_add(&bar[XB_XGEN(b.x)], 1u);
;             asm volatile("s_waitcnt vmcnt(0)" ::: "memory");
.LBB0_708:
	s_or_b64 exec, exec, s[4:5]
	s_mov_b64 s[4:5], exec
	v_mbcnt_lo_u32_b32 v0, s4, 0
	v_mbcnt_hi_u32_b32 v0, s5, v0
	v_cmp_eq_u32_e32 vcc, 0, v0
	s_waitcnt vmcnt(0)
	s_and_saveexec_b64 s[6:7], vcc
	s_cbranch_execz .LBB0_710
	s_bcnt1_i32_b64 s4, s[4:5]
	v_readlane_b32 s0, v245, 13
	v_mov_b32_e32 v0, s4
	v_readlane_b32 s1, v245, 14
	s_nop 4
.LBB0_710:
	s_or_b64 exec, exec, s[6:7]
	s_waitcnt vmcnt(0)

; __device__ __forceinline__ unsigned xb_ld(unsigned* p)              { return __hip_atomic_load(p, __ATOMIC_RELAXED, __HIP_MEMORY_SCOPE_AGENT); }
; __device__ __forceinline__ unsigned xb_add(unsigned* p, unsigned v) { return __hip_atomic_fetch_add(p, v, __ATOMIC_RELAXED, __HIP_MEMORY_SCOPE_AGENT); }
; #define XB_SPIN(cond, bar) do { unsigned _sp = 0; while (cond) { \
;     if ((++_sp & 255u) == 0u) { if (xb_ld(&(bar)[XB_TMO])) break; if (_sp > XB_SPIN_CAP) { atomicAdd(&(bar)[XB_TMO], 1u); break; } } } } while (0)
; __device__ __forceinline__ void xcd_barrier(const XcdBarrier& b) {
;     ...
;         if (old + 1u == (gen + 1u) * nloc) {
;             __builtin_amdgcn_fence(__ATOMIC_RELEASE, "agent");
;             asm volatile("s_waitcnt vmcnt(0)" ::: "memory");
;             const unsigned og = xb_add(&bar[XB_TOP], 1u);
;             const unsigned tg = og / nx;
;             if (og + 1u == (tg + 1u) * nx) xb_add(&bar[XB_TOPGEN], 1u);
;             else XB_SPIN(xb_ld(&bar[XB_TOPGEN]) == tg, bar);
;             __builtin_amdgcn_fence(__ATOMIC_ACQUIRE, "agent");
;             xb_add(&bar[XB_XGEN(b.x)], 1u);
;             asm volatile("s_waitcnt vmcnt(0)" ::: "memory");
.LBB0_770:
	s_or_b64 exec, exec, s[2:3]
	s_and_saveexec_b64 s[2:3], s[4:5]
	s_cbranch_execz .LBB0_772
	global_atomic_add v[0:1], v213, off
	v_readlane_b32 s98, v245, 17
	v_readlane_b32 s99, v245, 18
	s_nop 3
	s_sub_u32 s98, s98, 0x1100
	s_subb_u32 s99, s99, 0
	global_atomic_add v169, v213, s[98:99]
	global_atomic_add v169, v213, s[98:99] offset:256
	global_atomic_add v169, v213, s[98:99] offset:512
	global_atomic_add v169, v213, s[98:99] offset:768
	global_atomic_add v169, v213, s[98:99] offset:1024
	global_atomic_add v169, v213, s[98:99] offset:1280
	global_atomic_add v169, v213, s[98:99] offset:1536
	global_atomic_add v169, v213, s[98:99] offset:1792
	global_atomic_add v169, v213, s[98:99] offset:2048
	global_atomic_add v169, v213, s[98:99] offset:2304
	global_atomic_add v169, v213, s[98:99] offset:2560
	global_atomic_add v169, v213, s[98:99] offset:2816
	global_atomic_add v169, v213, s[98:99] offset:3072
	global_atomic_add v169, v213, s[98:99] offset:3328
	global_atomic_add v169, v213, s[98:99] offset:3584
	global_atomic_add v169, v213, s[98:99] offset:3840
.LBB0_772:
	s_or_b64 exec, exec, s[2:3]
	s_mov_b64 s[2:3], exec
	v_mbcnt_lo_u32_b32 v0, s2, 0
	v_mbcnt_hi_u32_b32 v0, s3, v0
	v_cmp_eq_u32_e32 vcc, 0, v0
	s_waitcnt vmcnt(0)
	s_and_saveexec_b64 s[4:5], vcc
	s_cbranch_execz .LBB0_774
	s_bcnt1_i32_b64 s2, s[2:3]
	v_mov_b32_e32 v0, s2
	v_readlane_b32 s2, v245, 13
	v_readlane_b32 s3, v245, 14
	s_nop 4
.LBB0_774:
	s_or_b64 exec, exec, s[4:5]
	s_waitcnt vmcnt(0)

; __device__ __forceinline__ unsigned xb_ld(unsigned* p)              { return __hip_atomic_load(p, __ATOMIC_RELAXED, __HIP_MEMORY_SCOPE_AGENT); }
; __device__ __forceinline__ unsigned xb_add(unsigned* p, unsigned v) { return __hip_atomic_fetch_add(p, v, __ATOMIC_RELAXED, __HIP_MEMORY_SCOPE_AGENT); }
; #define XB_SPIN(cond, bar) do { unsigned _sp = 0; while (cond) { \
;     if ((++_sp & 255u) == 0u) { if (xb_ld(&(bar)[XB_TMO])) break; if (_sp > XB_SPIN_CAP) { atomicAdd(&(bar)[XB_TMO], 1u); break; } } } } while (0)
; __device__ __forceinline__ void xcd_barrier(const XcdBarrier& b) {
;     ...
;         if (old + 1u == (gen + 1u) * nloc) {
;             __builtin_amdgcn_fence(__ATOMIC_RELEASE, "agent");
;             asm volatile("s_waitcnt vmcnt(0)" ::: "memory");
;             const unsigned og = xb_add(&bar[XB_TOP], 1u);
;             const unsigned tg = og / nx;
;             if (og + 1u == (tg + 1u) * nx) xb_add(&bar[XB_TOPGEN], 1u);
;             else XB_SPIN(xb_ld(&bar[XB_TOPGEN]) == tg, bar);
;             __builtin_amdgcn_fence(__ATOMIC_ACQUIRE, "agent");
;             xb_add(&bar[XB_XGEN(b.x)], 1u);
;             asm volatile("s_waitcnt vmcnt(0)" ::: "memory");
.LBB0_869:
	s_or_b64 exec, exec, s[4:5]
	s_mov_b64 s[4:5], exec
	v_mbcnt_lo_u32_b32 v0, s4, 0
	v_mbcnt_hi_u32_b32 v0, s5, v0
	v_cmp_eq_u32_e32 vcc, 0, v0
	s_waitcnt vmcnt(0)
	s_and_saveexec_b64 s[6:7], vcc
	s_cbranch_execz .LBB0_871
	s_bcnt1_i32_b64 s4, s[4:5]
	v_mov_b32_e32 v0, s4
	v_readlane_b32 s4, v245, 13
	v_readlane_b32 s5, v245, 14
	s_nop 4
.LBB0_871:
	s_or_b64 exec, exec, s[6:7]
	s_waitcnt vmcnt(0)

; __device__ __forceinline__ unsigned xb_ld(unsigned* p)              { return __hip_atomic_load(p, __ATOMIC_RELAXED, __HIP_MEMORY_SCOPE_AGENT); }
; __device__ __forceinline__ unsigned xb_add(unsigned* p, unsigned v) { return __hip_atomic_fetch_add(p, v, __ATOMIC_RELAXED, __HIP_MEMORY_SCOPE_AGENT); }
; #define XB_SPIN(cond, bar) do { unsigned _sp = 0; while (cond) { \
;     if ((++_sp & 255u) == 0u) { if (xb_ld(&(bar)[XB_TMO])) break; if (_sp > XB_SPIN_CAP) { atomicAdd(&(bar)[XB_TMO], 1u); break; } } } } while (0)
; __device__ __forceinline__ void xcd_barrier(const XcdBarrier& b) {
;     ...
;         if (old + 1u == (gen + 1u) * nloc) {
;             __builtin_amdgcn_fence(__ATOMIC_RELEASE, "agent");
;             asm volatile("s_waitcnt vmcnt(0)" ::: "memory");
;             const unsigned og = xb_add(&bar[XB_TOP], 1u);
;             const unsigned tg = og / nx;
;             if (og + 1u == (tg + 1u) * nx) xb_add(&bar[XB_TOPGEN], 1u);
;             else XB_SPIN(xb_ld(&bar[XB_TOPGEN]) == tg, bar);
;             __builtin_amdgcn_fence(__ATOMIC_ACQUIRE, "agent");
;             xb_add(&bar[XB_XGEN(b.x)], 1u);
;             asm volatile("s_waitcnt vmcnt(0)" ::: "memory");
.LBB0_1009:
	s_or_b64 exec, exec, s[2:3]
	s_mov_b64 s[2:3], exec
	v_mbcnt_lo_u32_b32 v0, s2, 0
	v_mbcnt_hi_u32_b32 v0, s3, v0
	v_cmp_eq_u32_e32 vcc, 0, v0
	s_waitcnt vmcnt(0)
	s_and_saveexec_b64 s[4:5], vcc
	s_cbranch_execz .LBB0_1011
	s_bcnt1_i32_b64 s2, s[2:3]
	v_mov_b32_e32 v0, s2
	v_readlane_b32 s2, v245, 13
	v_readlane_b32 s3, v245, 14
	s_nop 4
.LBB0_1011:
	s_or_b64 exec, exec, s[4:5]
	s_waitcnt vmcnt(0)

; __device__ __forceinline__ unsigned xb_ld(unsigned* p)              { return __hip_atomic_load(p, __ATOMIC_RELAXED, __HIP_MEMORY_SCOPE_AGENT); }
; __device__ __forceinline__ unsigned xb_add(unsigned* p, unsigned v) { return __hip_atomic_fetch_add(p, v, __ATOMIC_RELAXED, __HIP_MEMORY_SCOPE_AGENT); }
; #define XB_SPIN(cond, bar) do { unsigned _sp = 0; while (cond) { \
;     if ((++_sp & 255u) == 0u) { if (xb_ld(&(bar)[XB_TMO])) break; if (_sp > XB_SPIN_CAP) { atomicAdd(&(bar)[XB_TMO], 1u); break; } } } } while (0)
; __device__ __forceinline__ void xcd_barrier(const XcdBarrier& b) {
;     ...
;         if (old + 1u == (gen + 1u) * nloc) {
;             __builtin_amdgcn_fence(__ATOMIC_RELEASE, "agent");
;             asm volatile("s_waitcnt vmcnt(0)" ::: "memory");
;             const unsigned og = xb_add(&bar[XB_TOP], 1u);
;             const unsigned tg = og / nx;
;             if (og + 1u == (tg + 1u) * nx) xb_add(&bar[XB_TOPGEN], 1u);
;             else XB_SPIN(xb_ld(&bar[XB_TOPGEN]) == tg, bar);
;             __builtin_amdgcn_fence(__ATOMIC_ACQUIRE, "agent");
;             xb_add(&bar[XB_XGEN(b.x)], 1u);
;             asm volatile("s_waitcnt vmcnt(0)" ::: "memory");
.LBB0_1070:
	s_or_b64 exec, exec, s[2:3]
	s_mov_b64 s[2:3], exec
	v_mbcnt_lo_u32_b32 v0, s2, 0
	v_mbcnt_hi_u32_b32 v0, s3, v0
	v_cmp_eq_u32_e32 vcc, 0, v0
	s_waitcnt vmcnt(0)
	s_and_saveexec_b64 s[4:5], vcc
	s_cbranch_execz .LBB0_238
	s_bcnt1_i32_b64 s2, s[2:3]
	v_mov_b32_e32 v0, s2
	v_readlane_b32 s2, v245, 13
	v_readlane_b32 s3, v245, 14
	s_nop 4
	s_branch .LBB0_238
